# second co-resident block delayed ~16us at the start of the GU GEMM phase (stagger epilogues against the other block's main loop)
# baseline (speedup 1.0000x reference)
.LBB0_1029:
	s_or_b64 exec, exec, s[0:1]
	v_readlane_b32 s0, v253, 0
	s_waitcnt lgkmcnt(0)
	s_barrier
	s_getreg_b32 s100, hwreg(HW_REG_LDS_ALLOC, 0, 8)
	s_cmp_eq_u32 s100, 0
	s_cbranch_scc1 .Lstag_1029_done
	s_sleep 127
	s_sleep 127
	s_sleep 127
	s_sleep 127
.Lstag_1029_done:
	s_ashr_i32 s2, s0, 3
	s_mul_i32 s3, s25, 44
	s_cmp_ge_i32 s2, s3
	s_cbranch_scc1 .LBB0_1034
	v_readlane_b32 s4, v254, 41
	s_mul_i32 s1, s4, 0xb00000
	v_readlane_b32 s5, v254, 42
	s_add_u32 s4, s52, s1
	s_addc_u32 s5, s53, 0
	s_and_b32 s6, s0, 7
	s_mul_i32 s6, s6, s25

	.amdhsa_kernel _Z11mega_kernel6Params
		.amdhsa_group_segment_fixed_size 65076
		.amdhsa_private_segment_fixed_size 0
		.amdhsa_kernarg_size 624
		.amdhsa_user_sgpr_count 2
		.amdhsa_user_sgpr_dispatch_ptr 0
		.amdhsa_user_sgpr_queue_ptr 0
		.amdhsa_user_sgpr_kernarg_segment_ptr 1
		.amdhsa_user_sgpr_dispatch_id 0
		.amdhsa_user_sgpr_kernarg_preload_length 0
		.amdhsa_user_sgpr_kernarg_preload_offset 0
		.amdhsa_user_sgpr_private_segment_size 0
		.amdhsa_uses_dynamic_stack 0
		.amdhsa_enable_private_segment 0
		.amdhsa_system_sgpr_workgroup_id_x 1
		.amdhsa_system_sgpr_workgroup_id_y 0
		.amdhsa_system_sgpr_workgroup_id_z 0
		.amdhsa_system_sgpr_workgroup_info 0
		.amdhsa_system_vgpr_workitem_id 2
		.amdhsa_next_free_vgpr 256
		.amdhsa_next_free_sgpr 102
		.amdhsa_accum_offset 256
		.amdhsa_reserve_vcc 1
		.amdhsa_float_round_mode_32 0
		.amdhsa_float_round_mode_16_64 0
		.amdhsa_float_denorm_mode_32 3
		.amdhsa_float_denorm_mode_16_64 3
		.amdhsa_dx10_clamp 1
		.amdhsa_ieee_mode 1
		.amdhsa_fp16_overflow 0
		.amdhsa_tg_split 0
		.amdhsa_exception_fp_ieee_invalid_op 0
		.amdhsa_exception_fp_denorm_src 0
		.amdhsa_exception_fp_ieee_div_zero 0
		.amdhsa_exception_fp_ieee_overflow 0
		.amdhsa_exception_fp_ieee_underflow 0
		.amdhsa_exception_fp_ieee_inexact 0
		.amdhsa_exception_int_div_zero 0
	.end_amdhsa_kernel

.Lfunc_end0:
	.size	_Z11mega_kernel6Params, .Lfunc_end0-_Z11mega_kernel6Params
	.set _Z11mega_kernel6Params.num_vgpr, 256
	.set _Z11mega_kernel6Params.num_agpr, 0
	.set _Z11mega_kernel6Params.numbered_sgpr, 102
	.set _Z11mega_kernel6Params.num_named_barrier, 0
	.set _Z11mega_kernel6Params.private_seg_size, 0
	.set _Z11mega_kernel6Params.uses_vcc, 1
	.set _Z11mega_kernel6Params.uses_flat_scratch, 0
	.set _Z11mega_kernel6Params.has_dyn_sized_stack, 0
	.set _Z11mega_kernel6Params.has_recursion, 0
	.set _Z11mega_kernel6Params.has_indirect_call, 0

amdhsa.kernels:
  - .agpr_count:     0
    .args:
      - .offset:         0
        .size:           368
        .value_kind:     by_value
      - .offset:         368
        .size:           4
        .value_kind:     hidden_block_count_x
      - .offset:         372
        .size:           4
        .value_kind:     hidden_block_count_y
      - .offset:         376
        .size:           4
        .value_kind:     hidden_block_count_z
      - .offset:         380
        .size:           2
        .value_kind:     hidden_group_size_x
      - .offset:         382
        .size:           2
        .value_kind:     hidden_group_size_y
      - .offset:         384
        .size:           2
        .value_kind:     hidden_group_size_z
      - .offset:         386
        .size:           2
        .value_kind:     hidden_remainder_x
      - .offset:         388
        .size:           2
        .value_kind:     hidden_remainder_y
      - .offset:         390
        .size:           2
        .value_kind:     hidden_remainder_z
      - .offset:         408
        .size:           8
        .value_kind:     hidden_global_offset_x
      - .offset:         416
        .size:           8
        .value_kind:     hidden_global_offset_y
      - .offset:         424
        .size:           8
        .value_kind:     hidden_global_offset_z
      - .offset:         432
        .size:           2
        .value_kind:     hidden_grid_dims
      - .offset:         456
        .size:           8
        .value_kind:     hidden_multigrid_sync_arg
    .group_segment_fixed_size: 65076
    .kernarg_segment_align: 8
    .kernarg_segment_size: 624
    .language:       OpenCL C
    .language_version:
      - 2
      - 0
    .max_flat_workgroup_size: 256
    .name:           _Z11mega_kernel6Params
    .private_segment_fixed_size: 0
    .sgpr_count:     108
    .sgpr_spill_count: 139
    .symbol:         _Z11mega_kernel6Params.kd
    .uniform_work_group_size: 1
    .uses_dynamic_stack: false
    .vgpr_count:     256
    .vgpr_spill_count: 0
    .wavefront_size: 64
